# RG-LRU phase conv: all input rows requested after the chunk-top barrier, 16 tokens evaluated as four interleaved FMA chains at a time
# speedup vs baseline: 1.0054x; 1.0054x over previous
.LBB0_383:
	s_or_b64 exec, exec, s[0:1]
	s_add_i32 s10, s33, 1
	v_cmp_lt_u32_e64 s[0:1], s10, v194
	s_waitcnt vmcnt(0)
	v_mov_b32_e32 v137, v119
	v_mov_b32_e32 v136, v118
	v_mov_b64_e32 v[132:133], v[130:131]
	v_mov_b64_e32 v[134:135], v[124:125]
	s_waitcnt lgkmcnt(0)
	s_barrier
	ds_read_b32 v218, v151
	ds_read2_b32 v[216:217], v152 offset0:44 offset1:88
	ds_read_b32 v219, v152 offset:528
	ds_read_b32 v220, v155 offset:528
	ds_read_b32 v221, v157 offset:528
	ds_read_b32 v222, v158 offset:528
	ds_read_b32 v223, v159 offset:528
	ds_read_b32 v224, v160 offset:528
	ds_read_b32 v225, v161 offset:528
	ds_read_b32 v226, v162 offset:528
	ds_read_b32 v227, v163 offset:528
	ds_read_b32 v228, v164 offset:528
	ds_read_b32 v229, v165 offset:528
	ds_read_b32 v230, v166 offset:528
	ds_read_b32 v231, v167 offset:528
	ds_read_b32 v232, v168 offset:528
	ds_read_b32 v233, v169 offset:528
	ds_read_b32 v234, v170 offset:528
	s_and_saveexec_b64 s[52:53], s[0:1]
	s_cbranch_execz .LBB0_403
	v_mov_b32_e32 v2, v1
	v_mov_b32_e32 v3, v1
	s_lshl_b32 s74, s10, 6
	v_mov_b32_e32 v0, v1
	v_mov_b64_e32 v[14:15], v[2:3]
	s_add_i32 s11, s74, -3
	v_mov_b64_e32 v[12:13], v[0:1]
	s_and_saveexec_b64 s[50:51], s[8:9]
	s_cbranch_execz .LBB0_388
	v_mov_b32_e32 v2, v1
	v_mov_b32_e32 v3, v1
	v_add_u32_e32 v16, s11, v140
	v_mov_b32_e32 v0, v1
	v_mov_b64_e32 v[14:15], v[2:3]
	v_cmp_lt_u32_e64 s[0:1], v16, v83
	v_mov_b64_e32 v[12:13], v[0:1]
	s_and_saveexec_b64 s[72:73], s[0:1]
	s_cbranch_execz .LBB0_387
	v_add_u32_e32 v0, v16, v192
	v_mad_u64_u32 v[2:3], s[0:1], v0, s78, v[106:107]
	global_load_dwordx4 v[12:15], v[2:3], off

.LBB0_403:
	s_or_b64 exec, exec, s[52:53]
	s_and_saveexec_b64 s[0:1], s[6:7]
	s_cbranch_execz .LBB0_436
	s_waitcnt lgkmcnt(0)
	v_lshlrev_b32_e32 v236, 16, v218
	v_and_b32_e32 v237, 0xffff0000, v218
	v_lshlrev_b32_e32 v238, 16, v216
	v_and_b32_e32 v239, 0xffff0000, v216
	v_lshlrev_b32_e32 v240, 16, v217
	v_and_b32_e32 v241, 0xffff0000, v217
	v_lshlrev_b32_e32 v242, 16, v219
	v_and_b32_e32 v243, 0xffff0000, v219
	v_lshlrev_b32_e32 v244, 16, v220
	v_and_b32_e32 v245, 0xffff0000, v220
	v_lshlrev_b32_e32 v246, 16, v221
	v_and_b32_e32 v247, 0xffff0000, v221
	v_lshlrev_b32_e32 v248, 16, v222
	v_and_b32_e32 v249, 0xffff0000, v222
	v_pk_fma_f32 v[24:25], v[96:97], v[236:237], v[104:105]
	v_pk_fma_f32 v[26:27], v[96:97], v[238:239], v[104:105]
	v_pk_fma_f32 v[28:29], v[96:97], v[240:241], v[104:105]
	v_pk_fma_f32 v[30:31], v[96:97], v[242:243], v[104:105]
	v_pk_fma_f32 v[24:25], v[100:101], v[238:239], v[24:25]
	v_pk_fma_f32 v[26:27], v[100:101], v[240:241], v[26:27]
	v_pk_fma_f32 v[28:29], v[100:101], v[242:243], v[28:29]
	v_pk_fma_f32 v[30:31], v[100:101], v[244:245], v[30:31]
	v_pk_fma_f32 v[24:25], v[102:103], v[240:241], v[24:25]
	v_pk_fma_f32 v[26:27], v[102:103], v[242:243], v[26:27]
	v_pk_fma_f32 v[28:29], v[102:103], v[244:245], v[28:29]
	v_pk_fma_f32 v[30:31], v[102:103], v[246:247], v[30:31]
	v_pk_fma_f32 v[24:25], v[98:99], v[242:243], v[24:25]
	v_pk_fma_f32 v[26:27], v[98:99], v[244:245], v[26:27]
	v_pk_fma_f32 v[28:29], v[98:99], v[246:247], v[28:29]
	v_pk_fma_f32 v[30:31], v[98:99], v[248:249], v[30:31]
	v_cvt_pk_bf16_f32 v0, v24, v25
	v_cvt_pk_bf16_f32 v2, v26, v27
	v_cvt_pk_bf16_f32 v3, v28, v29
	v_cvt_pk_bf16_f32 v235, v30, v31
	ds_write_b32 v175, v0 offset:11808
	ds_write_b32 v187, v2 offset:11808
	ds_write_b32 v187, v3 offset:12016
	ds_write_b32 v187, v235 offset:12224
	s_and_saveexec_b64 s[50:51], s[42:43]
	ds_write_b64 v91, v[24:25] offset:25120
	ds_write_b64 v205, v[26:27] offset:25120
	ds_write_b64 v205, v[28:29] offset:25312
	ds_write_b64 v205, v[30:31] offset:25504
	s_or_b64 exec, exec, s[50:51]
	v_lshlrev_b32_e32 v250, 16, v223
	v_and_b32_e32 v251, 0xffff0000, v223
	v_lshlrev_b32_e32 v236, 16, v224
	v_and_b32_e32 v237, 0xffff0000, v224
	v_lshlrev_b32_e32 v238, 16, v225
	v_and_b32_e32 v239, 0xffff0000, v225
	v_lshlrev_b32_e32 v240, 16, v226
	v_and_b32_e32 v241, 0xffff0000, v226
	v_pk_fma_f32 v[24:25], v[96:97], v[244:245], v[104:105]
	v_pk_fma_f32 v[26:27], v[96:97], v[246:247], v[104:105]
	v_pk_fma_f32 v[28:29], v[96:97], v[248:249], v[104:105]
	v_pk_fma_f32 v[30:31], v[96:97], v[250:251], v[104:105]
	v_pk_fma_f32 v[24:25], v[100:101], v[246:247], v[24:25]
	v_pk_fma_f32 v[26:27], v[100:101], v[248:249], v[26:27]
	v_pk_fma_f32 v[28:29], v[100:101], v[250:251], v[28:29]
	v_pk_fma_f32 v[30:31], v[100:101], v[236:237], v[30:31]
	v_pk_fma_f32 v[24:25], v[102:103], v[248:249], v[24:25]
	v_pk_fma_f32 v[26:27], v[102:103], v[250:251], v[26:27]
	v_pk_fma_f32 v[28:29], v[102:103], v[236:237], v[28:29]
	v_pk_fma_f32 v[30:31], v[102:103], v[238:239], v[30:31]
	v_pk_fma_f32 v[24:25], v[98:99], v[250:251], v[24:25]
	v_pk_fma_f32 v[26:27], v[98:99], v[236:237], v[26:27]
	v_pk_fma_f32 v[28:29], v[98:99], v[238:239], v[28:29]
	v_pk_fma_f32 v[30:31], v[98:99], v[240:241], v[30:31]
	v_cvt_pk_bf16_f32 v0, v24, v25
	v_cvt_pk_bf16_f32 v2, v26, v27
	v_cvt_pk_bf16_f32 v3, v28, v29
	v_cvt_pk_bf16_f32 v235, v30, v31
	ds_write_b32 v187, v0 offset:12432
	ds_write_b32 v187, v2 offset:12640
	ds_write_b32 v187, v3 offset:12848
	ds_write_b32 v187, v235 offset:13056
	s_and_saveexec_b64 s[50:51], s[42:43]
	ds_write_b64 v205, v[24:25] offset:25696
	ds_write_b64 v205, v[26:27] offset:25888
	ds_write_b64 v205, v[28:29] offset:26080
	ds_write_b64 v205, v[30:31] offset:26272
	s_or_b64 exec, exec, s[50:51]
	v_lshlrev_b32_e32 v242, 16, v227
	v_and_b32_e32 v243, 0xffff0000, v227
	v_lshlrev_b32_e32 v244, 16, v228
	v_and_b32_e32 v245, 0xffff0000, v228
	v_lshlrev_b32_e32 v246, 16, v229
	v_and_b32_e32 v247, 0xffff0000, v229
	v_lshlrev_b32_e32 v248, 16, v230
	v_and_b32_e32 v249, 0xffff0000, v230
	v_pk_fma_f32 v[24:25], v[96:97], v[236:237], v[104:105]
	v_pk_fma_f32 v[26:27], v[96:97], v[238:239], v[104:105]
	v_pk_fma_f32 v[28:29], v[96:97], v[240:241], v[104:105]
	v_pk_fma_f32 v[30:31], v[96:97], v[242:243], v[104:105]
	v_pk_fma_f32 v[24:25], v[100:101], v[238:239], v[24:25]
	v_pk_fma_f32 v[26:27], v[100:101], v[240:241], v[26:27]
	v_pk_fma_f32 v[28:29], v[100:101], v[242:243], v[28:29]
	v_pk_fma_f32 v[30:31], v[100:101], v[244:245], v[30:31]
	v_pk_fma_f32 v[24:25], v[102:103], v[240:241], v[24:25]
	v_pk_fma_f32 v[26:27], v[102:103], v[242:243], v[26:27]
	v_pk_fma_f32 v[28:29], v[102:103], v[244:245], v[28:29]
	v_pk_fma_f32 v[30:31], v[102:103], v[246:247], v[30:31]
	v_pk_fma_f32 v[24:25], v[98:99], v[242:243], v[24:25]
	v_pk_fma_f32 v[26:27], v[98:99], v[244:245], v[26:27]
	v_pk_fma_f32 v[28:29], v[98:99], v[246:247], v[28:29]
	v_pk_fma_f32 v[30:31], v[98:99], v[248:249], v[30:31]
	v_cvt_pk_bf16_f32 v0, v24, v25
	v_cvt_pk_bf16_f32 v2, v26, v27
	v_cvt_pk_bf16_f32 v3, v28, v29
	v_cvt_pk_bf16_f32 v235, v30, v31
	ds_write_b32 v187, v0 offset:13264
	ds_write_b32 v187, v2 offset:13472
	ds_write_b32 v187, v3 offset:13680
	ds_write_b32 v187, v235 offset:13888
	s_and_saveexec_b64 s[50:51], s[42:43]
	ds_write_b64 v205, v[24:25] offset:26464
	ds_write_b64 v205, v[26:27] offset:26656
	ds_write_b64 v205, v[28:29] offset:26848
	ds_write_b64 v205, v[30:31] offset:27040
	s_or_b64 exec, exec, s[50:51]
	v_lshlrev_b32_e32 v250, 16, v231
	v_and_b32_e32 v251, 0xffff0000, v231
	v_lshlrev_b32_e32 v236, 16, v232
	v_and_b32_e32 v237, 0xffff0000, v232
	v_lshlrev_b32_e32 v238, 16, v233
	v_and_b32_e32 v239, 0xffff0000, v233
	v_lshlrev_b32_e32 v240, 16, v234
	v_and_b32_e32 v241, 0xffff0000, v234
	v_pk_fma_f32 v[24:25], v[96:97], v[244:245], v[104:105]
	v_pk_fma_f32 v[26:27], v[96:97], v[246:247], v[104:105]
	v_pk_fma_f32 v[28:29], v[96:97], v[248:249], v[104:105]
	v_pk_fma_f32 v[30:31], v[96:97], v[250:251], v[104:105]
	v_pk_fma_f32 v[24:25], v[100:101], v[246:247], v[24:25]
	v_pk_fma_f32 v[26:27], v[100:101], v[248:249], v[26:27]
	v_pk_fma_f32 v[28:29], v[100:101], v[250:251], v[28:29]
	v_pk_fma_f32 v[30:31], v[100:101], v[236:237], v[30:31]
	v_pk_fma_f32 v[24:25], v[102:103], v[248:249], v[24:25]
	v_pk_fma_f32 v[26:27], v[102:103], v[250:251], v[26:27]
	v_pk_fma_f32 v[28:29], v[102:103], v[236:237], v[28:29]
	v_pk_fma_f32 v[30:31], v[102:103], v[238:239], v[30:31]
	v_pk_fma_f32 v[24:25], v[98:99], v[250:251], v[24:25]
	v_pk_fma_f32 v[26:27], v[98:99], v[236:237], v[26:27]
	v_pk_fma_f32 v[28:29], v[98:99], v[238:239], v[28:29]
	v_pk_fma_f32 v[30:31], v[98:99], v[240:241], v[30:31]
	v_cvt_pk_bf16_f32 v0, v24, v25
	v_cvt_pk_bf16_f32 v2, v26, v27
	v_cvt_pk_bf16_f32 v3, v28, v29
	v_cvt_pk_bf16_f32 v235, v30, v31
	ds_write_b32 v187, v0 offset:14096
	ds_write_b32 v187, v2 offset:14304
	ds_write_b32 v187, v3 offset:14512
	ds_write_b32 v187, v235 offset:14720
	s_and_saveexec_b64 s[50:51], s[42:43]
	ds_write_b64 v205, v[24:25] offset:27232
	ds_write_b64 v205, v[26:27] offset:27424
	ds_write_b64 v205, v[28:29] offset:27616
	ds_write_b64 v205, v[30:31] offset:27808
	s_or_b64 exec, exec, s[50:51]
